# memory attention tile: K / V^T fragments kept in flight (rotating pool), 3-op exp2 softmax, packed sums
# speedup vs baseline: 1.0182x; 1.0001x over previous
; #define LAS __attribute__((address_space(3)))
; __device__ __forceinline__ f32x4 mfma16(bf16x8 a, bf16x8 b, f32x4 c) { return __builtin_amdgcn_mfma_f32_16x16x32_bf16(a, b, c, 0, 0, 0); }
; __device__ __forceinline__ void xa_pair(LAS unsigned char* lds, const bf16_t* Ux, const bf16_t* Kb, const bf16_t* Vt, bf16_t* Yx, int pair, int tid) {
;     ...
;     for (int tq = 0; tq < 2; ++tq) {
;         const int t = b * SEQ + (blk0 + tq) * 128 + 16 * wave + fr;
;         bf16x8 qf[4];
; #pragma unroll
;         for (int ks = 0; ks < 4; ++ks) qf[ks] = *(const bf16x8*)(Ux + (size_t)t * 512 + h * 128 + ks * 32 + fq * 8);
;         f32x4 s[16];
; #pragma unroll
;         for (int nt = 0; nt < 16; ++nt) { s[nt] = (f32x4){0.f, 0.f, 0.f, 0.f}; LAS const unsigned char* kr = lds + (16 * nt + fr) * XK_STRIDE + fq * 16;
; #pragma unroll
;             for (int ks = 0; ks < 4; ++ks) s[nt] = mfma16(*(LAS const bf16x8*)(kr + ks * 64), qf[ks], s[nt]);
;             if (nt & 1) asm volatile("" ::: "memory"); }
.LBB0_318:
	v_add_u32_e32 v2, s8, v136
	v_ashrrev_i32_e32 v3, 31, v2
	v_lshlrev_b64 v[114:115], 10, v[2:3]
	v_lshl_add_u64 v[2:3], v[110:111], 0, v[114:115]
	global_load_dwordx4 v[74:77], v[2:3], off
	global_load_dwordx4 v[70:73], v[2:3], off offset:64
	global_load_dwordx4 v[66:69], v[2:3], off offset:128
	global_load_dwordx4 v[54:57], v[2:3], off offset:192
	s_mov_b32 s8, 0xf149f2ca
	ds_read_b128 v[164:167], v134
	ds_read_b128 v[168:171], v134 offset:64
	ds_read_b128 v[172:175], v134 offset:128
	ds_read_b128 v[176:179], v134 offset:192
	ds_read_b128 v[180:183], v134 offset:4352
	ds_read_b128 v[184:187], v134 offset:4416
	ds_read_b128 v[188:191], v134 offset:4480
	ds_read_b128 v[192:195], v134 offset:4544
	ds_read_b128 v[196:199], v134 offset:8704
	ds_read_b128 v[200:203], v134 offset:8768
	ds_read_b128 v[204:207], v134 offset:8832
	ds_read_b128 v[212:215], v134 offset:8896
	s_waitcnt vmcnt(0)
	s_waitcnt lgkmcnt(8)
	v_mfma_f32_16x16x32_bf16 v[58:61], v[164:167], v[74:77], 0
	v_mfma_f32_16x16x32_bf16 v[58:61], v[168:171], v[70:73], v[58:61]
	v_mfma_f32_16x16x32_bf16 v[58:61], v[172:175], v[66:69], v[58:61]
	v_mfma_f32_16x16x32_bf16 v[58:61], v[176:179], v[54:57], v[58:61]
	ds_read_b128 v[164:167], v134 offset:13056
	ds_read_b128 v[168:171], v134 offset:13120
	ds_read_b128 v[172:175], v134 offset:13184
	ds_read_b128 v[176:179], v134 offset:13248
	s_waitcnt lgkmcnt(8)
	v_mfma_f32_16x16x32_bf16 v[46:49], v[180:183], v[74:77], 0
	v_mfma_f32_16x16x32_bf16 v[46:49], v[184:187], v[70:73], v[46:49]
	v_mfma_f32_16x16x32_bf16 v[46:49], v[188:191], v[66:69], v[46:49]
	v_mfma_f32_16x16x32_bf16 v[46:49], v[192:195], v[54:57], v[46:49]
	ds_read_b128 v[180:183], v134 offset:17408
	ds_read_b128 v[184:187], v134 offset:17472
	ds_read_b128 v[188:191], v134 offset:17536
	ds_read_b128 v[192:195], v134 offset:17600
	s_waitcnt lgkmcnt(8)
	v_mfma_f32_16x16x32_bf16 v[62:65], v[196:199], v[74:77], 0
	v_mfma_f32_16x16x32_bf16 v[62:65], v[200:203], v[70:73], v[62:65]
	v_mfma_f32_16x16x32_bf16 v[62:65], v[204:207], v[66:69], v[62:65]
	v_mfma_f32_16x16x32_bf16 v[62:65], v[212:215], v[54:57], v[62:65]
	ds_read_b128 v[196:199], v134 offset:21760
	ds_read_b128 v[200:203], v134 offset:21824
	ds_read_b128 v[204:207], v134 offset:21888
	ds_read_b128 v[212:215], v134 offset:21952
	s_waitcnt lgkmcnt(8)
	v_mfma_f32_16x16x32_bf16 v[50:53], v[164:167], v[74:77], 0
	v_mfma_f32_16x16x32_bf16 v[50:53], v[168:171], v[70:73], v[50:53]
	v_mfma_f32_16x16x32_bf16 v[50:53], v[172:175], v[66:69], v[50:53]
	v_mfma_f32_16x16x32_bf16 v[50:53], v[176:179], v[54:57], v[50:53]
	ds_read_b128 v[164:167], v134 offset:26112
	ds_read_b128 v[168:171], v134 offset:26176
	ds_read_b128 v[172:175], v134 offset:26240
	ds_read_b128 v[176:179], v134 offset:26304
	s_waitcnt lgkmcnt(8)
	v_mfma_f32_16x16x32_bf16 v[42:45], v[180:183], v[74:77], 0
	v_mfma_f32_16x16x32_bf16 v[42:45], v[184:187], v[70:73], v[42:45]
	v_mfma_f32_16x16x32_bf16 v[42:45], v[188:191], v[66:69], v[42:45]
	v_mfma_f32_16x16x32_bf16 v[42:45], v[192:195], v[54:57], v[42:45]
	ds_read_b128 v[180:183], v134 offset:30464
	ds_read_b128 v[184:187], v134 offset:30528
	ds_read_b128 v[188:191], v134 offset:30592
	ds_read_b128 v[192:195], v134 offset:30656
	s_waitcnt lgkmcnt(8)
	v_mfma_f32_16x16x32_bf16 v[38:41], v[196:199], v[74:77], 0
	v_mfma_f32_16x16x32_bf16 v[38:41], v[200:203], v[70:73], v[38:41]
	v_mfma_f32_16x16x32_bf16 v[38:41], v[204:207], v[66:69], v[38:41]
	v_mfma_f32_16x16x32_bf16 v[38:41], v[212:215], v[54:57], v[38:41]
	ds_read_b128 v[196:199], v134 offset:34816
	ds_read_b128 v[200:203], v134 offset:34880
	ds_read_b128 v[204:207], v134 offset:34944
	ds_read_b128 v[212:215], v134 offset:35008
	s_waitcnt lgkmcnt(8)
	v_mfma_f32_16x16x32_bf16 v[34:37], v[164:167], v[74:77], 0
	v_mfma_f32_16x16x32_bf16 v[34:37], v[168:171], v[70:73], v[34:37]
	v_mfma_f32_16x16x32_bf16 v[34:37], v[172:175], v[66:69], v[34:37]
	v_mfma_f32_16x16x32_bf16 v[34:37], v[176:179], v[54:57], v[34:37]
	ds_read_b128 v[164:167], v134 offset:39168
	ds_read_b128 v[168:171], v134 offset:39232
	ds_read_b128 v[172:175], v134 offset:39296
	ds_read_b128 v[176:179], v134 offset:39360
	s_waitcnt lgkmcnt(8)
	v_mfma_f32_16x16x32_bf16 v[30:33], v[180:183], v[74:77], 0
	v_mfma_f32_16x16x32_bf16 v[30:33], v[184:187], v[70:73], v[30:33]
	v_mfma_f32_16x16x32_bf16 v[30:33], v[188:191], v[66:69], v[30:33]
	v_mfma_f32_16x16x32_bf16 v[30:33], v[192:195], v[54:57], v[30:33]
	ds_read_b128 v[180:183], v134 offset:43520
	ds_read_b128 v[184:187], v134 offset:43584
	ds_read_b128 v[188:191], v134 offset:43648
	ds_read_b128 v[192:195], v134 offset:43712
	s_waitcnt lgkmcnt(8)
	v_mfma_f32_16x16x32_bf16 v[26:29], v[196:199], v[74:77], 0
	v_mfma_f32_16x16x32_bf16 v[26:29], v[200:203], v[70:73], v[26:29]
	v_mfma_f32_16x16x32_bf16 v[26:29], v[204:207], v[66:69], v[26:29]
	v_mfma_f32_16x16x32_bf16 v[26:29], v[212:215], v[54:57], v[26:29]
	ds_read_b128 v[196:199], v134 offset:47872
	ds_read_b128 v[200:203], v134 offset:47936
	ds_read_b128 v[204:207], v134 offset:48000
	ds_read_b128 v[212:215], v134 offset:48064
	s_waitcnt lgkmcnt(8)
	v_mfma_f32_16x16x32_bf16 v[22:25], v[164:167], v[74:77], 0
	v_mfma_f32_16x16x32_bf16 v[22:25], v[168:171], v[70:73], v[22:25]
	v_mfma_f32_16x16x32_bf16 v[22:25], v[172:175], v[66:69], v[22:25]
	v_mfma_f32_16x16x32_bf16 v[22:25], v[176:179], v[54:57], v[22:25]
	ds_read_b128 v[164:167], v134 offset:52224
	ds_read_b128 v[168:171], v134 offset:52288
	ds_read_b128 v[172:175], v134 offset:52352
	ds_read_b128 v[176:179], v134 offset:52416
	s_waitcnt lgkmcnt(8)
; #define LAS __attribute__((address_space(3)))
; __device__ __forceinline__ f32x4 mfma16(bf16x8 a, bf16x8 b, f32x4 c) { return __builtin_amdgcn_mfma_f32_16x16x32_bf16(a, b, c, 0, 0, 0); }
; __device__ __forceinline__ void xa_pair(LAS unsigned char* lds, const bf16_t* Ux, const bf16_t* Kb, const bf16_t* Vt, bf16_t* Yx, int pair, int tid) {
;     ...
;         for (int nt = 0; nt < 16; ++nt) { s[nt] = (f32x4){0.f, 0.f, 0.f, 0.f}; LAS const unsigned char* kr = lds + (16 * nt + fr) * XK_STRIDE + fq * 16;
; #pragma unroll
;             for (int ks = 0; ks < 4; ++ks) s[nt] = mfma16(*(LAS const bf16x8*)(kr + ks * 64), qf[ks], s[nt]);
;             if (nt & 1) asm volatile("" ::: "memory"); }
;         float mx = -1e30f;
; #pragma unroll
;         for (int nt = 0; nt < 16; ++nt)
; #pragma unroll
;             for (int j = 0; j < 4; ++j) mx = fmaxf(mx, s[nt][j]);
;         mx = fmaxf(mx, __shfl_xor(mx, 16)); mx = fmaxf(mx, __shfl_xor(mx, 32));
;         const float sc = 0.08838834764831845f * 1.4426950408889634f; float l = 0.f;
; #pragma unroll
;         for (int nt = 0; nt < 16; ++nt)
; #pragma unroll
;             for (int j = 0; j < 4; ++j) { const float pz = exp2f((s[nt][j] - mx) * sc); s[nt][j] = pz; l += pz; }
;     ...
;             for (int dt = 0; dt < 8; ++dt) { LAS const unsigned char* vr = lds + XV_OFF + (16 * dt + fr) * XV_STRIDE + (32 * c + 4 * fq) * 2; union { u32x4 u; bf16x8 v; } vf;
;                 const u32x2 lo = *(LAS const u32x2*)vr, hi = *(LAS const u32x2*)(vr + 32); vf.u.x = lo.x; vf.u.y = lo.y; vf.u.z = hi.x; vf.u.w = hi.y;
	v_mfma_f32_16x16x32_bf16 v[18:21], v[180:183], v[74:77], 0
	v_mfma_f32_16x16x32_bf16 v[18:21], v[184:187], v[70:73], v[18:21]
	v_mfma_f32_16x16x32_bf16 v[18:21], v[188:191], v[66:69], v[18:21]
	v_mfma_f32_16x16x32_bf16 v[18:21], v[192:195], v[54:57], v[18:21]
	ds_read_b128 v[180:183], v134 offset:56576
	ds_read_b128 v[184:187], v134 offset:56640
	ds_read_b128 v[188:191], v134 offset:56704
	ds_read_b128 v[192:195], v134 offset:56768
	s_waitcnt lgkmcnt(8)
	v_mfma_f32_16x16x32_bf16 v[10:13], v[196:199], v[74:77], 0
	v_mfma_f32_16x16x32_bf16 v[10:13], v[200:203], v[70:73], v[10:13]
	v_mfma_f32_16x16x32_bf16 v[10:13], v[204:207], v[66:69], v[10:13]
	v_mfma_f32_16x16x32_bf16 v[10:13], v[212:215], v[54:57], v[10:13]
	ds_read_b128 v[196:199], v134 offset:60928
	ds_read_b128 v[200:203], v134 offset:60992
	ds_read_b128 v[204:207], v134 offset:61056
	ds_read_b128 v[212:215], v134 offset:61120
	s_waitcnt lgkmcnt(8)
	v_mfma_f32_16x16x32_bf16 v[2:5], v[164:167], v[74:77], 0
	v_mfma_f32_16x16x32_bf16 v[2:5], v[168:171], v[70:73], v[2:5]
	v_mfma_f32_16x16x32_bf16 v[2:5], v[172:175], v[66:69], v[2:5]
	v_mfma_f32_16x16x32_bf16 v[2:5], v[176:179], v[54:57], v[2:5]
	ds_read_b128 v[164:167], v134 offset:65280
	ds_read_b128 v[168:171], v134 offset:65344
	ds_read_b128 v[172:175], v134 offset:65408
	ds_read_b128 v[176:179], v134 offset:65472
	s_waitcnt lgkmcnt(8)
	v_mfma_f32_16x16x32_bf16 v[14:17], v[180:183], v[74:77], 0
	v_mfma_f32_16x16x32_bf16 v[14:17], v[184:187], v[70:73], v[14:17]
	v_mfma_f32_16x16x32_bf16 v[14:17], v[188:191], v[66:69], v[14:17]
	v_mfma_f32_16x16x32_bf16 v[14:17], v[192:195], v[54:57], v[14:17]
	s_waitcnt lgkmcnt(4)
	v_mfma_f32_16x16x32_bf16 v[6:9], v[196:199], v[74:77], 0
	v_mfma_f32_16x16x32_bf16 v[6:9], v[200:203], v[70:73], v[6:9]
	v_mfma_f32_16x16x32_bf16 v[6:9], v[204:207], v[66:69], v[6:9]
	v_mfma_f32_16x16x32_bf16 v[6:9], v[212:215], v[54:57], v[6:9]
	s_waitcnt lgkmcnt(0)
	v_mfma_f32_16x16x32_bf16 v[216:219], v[164:167], v[74:77], 0
	v_mfma_f32_16x16x32_bf16 v[216:219], v[168:171], v[70:73], v[216:219]
	v_mfma_f32_16x16x32_bf16 v[216:219], v[172:175], v[66:69], v[216:219]
	v_mfma_f32_16x16x32_bf16 v[54:57], v[176:179], v[54:57], v[216:219]
	s_nop 7
	s_nop 2
	v_max3_f32 v66, v58, s8, v59
	v_max3_f32 v66, v66, v60, v61
	v_max3_f32 v66, v66, v46, v47
	v_max3_f32 v66, v66, v48, v49
	v_max3_f32 v66, v66, v62, v63
	v_max3_f32 v66, v66, v64, v65
	v_max3_f32 v66, v66, v50, v51
	v_max3_f32 v66, v66, v52, v53
	v_max3_f32 v66, v66, v42, v43
	v_max3_f32 v66, v66, v44, v45
	v_max3_f32 v66, v66, v38, v39
	v_max3_f32 v66, v66, v40, v41
	v_max3_f32 v66, v66, v34, v35
	v_max3_f32 v66, v66, v36, v37
	v_max3_f32 v66, v66, v30, v31
	v_max3_f32 v66, v66, v32, v33
	v_max3_f32 v66, v66, v26, v27
	v_max3_f32 v66, v66, v28, v29
	v_max3_f32 v66, v66, v22, v23
	v_max3_f32 v66, v66, v24, v25
	v_max3_f32 v66, v66, v18, v19
	v_max3_f32 v66, v66, v20, v21
	v_max3_f32 v66, v66, v10, v11
	v_max3_f32 v66, v66, v12, v13
	v_max3_f32 v66, v66, v2, v3
	v_max3_f32 v66, v66, v4, v5
	v_max3_f32 v66, v66, v14, v15
	v_max3_f32 v66, v66, v16, v17
	v_max3_f32 v66, v66, v6, v7
	v_max3_f32 v66, v66, v8, v9
	v_max3_f32 v66, v66, v54, v55
	v_max3_f32 v66, v66, v56, v57
	ds_bpermute_b32 v67, v124, v66
	s_waitcnt lgkmcnt(0)
	v_max_f32_e32 v67, v67, v67
	v_max_f32_e32 v66, v66, v67
	ds_bpermute_b32 v67, v125, v66
	s_waitcnt lgkmcnt(0)
	v_max_f32_e32 v67, v67, v67
	v_max_f32_e32 v140, v66, v67
	v_mov_b32_e32 v69, 0x3e0293ee
	v_mul_f32_e64 v67, -v140, v69
	v_mov_b32_e32 v220, v135
	v_add_u32_e32 v221, 0x2100, v135
	v_add_u32_e32 v222, 0x4200, v135
	v_add_u32_e32 v223, 0x6300, v135
	v_add_u32_e32 v224, 0x8400, v135
	v_add_u32_e32 v225, 0xa500, v135
	v_add_u32_e32 v226, 0xc600, v135
	v_add_u32_e32 v227, 0xe700, v135
	ds_read2_b64 v[164:167], v220 offset0:0 offset1:4
	ds_read2_b64 v[168:171], v221 offset0:0 offset1:4
	ds_read2_b64 v[172:175], v222 offset0:0 offset1:4
	ds_read2_b64 v[176:179], v223 offset0:0 offset1:4
	ds_read2_b64 v[180:183], v224 offset0:0 offset1:4
	ds_read2_b64 v[184:187], v225 offset0:0 offset1:4
	ds_read2_b64 v[188:191], v226 offset0:0 offset1:4
	ds_read2_b64 v[192:195], v227 offset0:0 offset1:4
	ds_read2_b64 v[196:199], v220 offset0:8 offset1:12
	ds_read2_b64 v[200:203], v221 offset0:8 offset1:12
	ds_read2_b64 v[204:207], v222 offset0:8 offset1:12
	ds_read2_b64 v[212:215], v223 offset0:8 offset1:12
	v_fma_f32 v58, v58, v69, v67
	v_fma_f32 v59, v59, v69, v67
	v_fma_f32 v60, v60, v69, v67
	v_fma_f32 v61, v61, v69, v67
	v_exp_f32_e32 v58, v58
	v_exp_f32_e32 v59, v59
	v_exp_f32_e32 v60, v60
	v_exp_f32_e32 v61, v61
	v_fma_f32 v46, v46, v69, v67
	v_fma_f32 v47, v47, v69, v67
	v_fma_f32 v48, v48, v69, v67
	v_fma_f32 v49, v49, v69, v67
	v_exp_f32_e32 v46, v46
	v_exp_f32_e32 v47, v47
	v_exp_f32_e32 v48, v48
	v_exp_f32_e32 v49, v49
	v_fma_f32 v62, v62, v69, v67
	v_fma_f32 v63, v63, v69, v67
	v_fma_f32 v64, v64, v69, v67
	v_fma_f32 v65, v65, v69, v67
	v_exp_f32_e32 v62, v62
	v_exp_f32_e32 v63, v63
	v_exp_f32_e32 v64, v64
	v_exp_f32_e32 v65, v65
	v_fma_f32 v50, v50, v69, v67
	v_fma_f32 v51, v51, v69, v67
	v_fma_f32 v52, v52, v69, v67
	v_fma_f32 v53, v53, v69, v67
	v_exp_f32_e32 v50, v50
	v_exp_f32_e32 v51, v51
	v_exp_f32_e32 v52, v52
	v_exp_f32_e32 v53, v53
	v_fma_f32 v42, v42, v69, v67
	v_fma_f32 v43, v43, v69, v67
	v_fma_f32 v44, v44, v69, v67
	v_fma_f32 v45, v45, v69, v67
	v_exp_f32_e32 v42, v42
	v_exp_f32_e32 v43, v43
	v_exp_f32_e32 v44, v44
	v_exp_f32_e32 v45, v45
	v_fma_f32 v38, v38, v69, v67
	v_fma_f32 v39, v39, v69, v67
	v_fma_f32 v40, v40, v69, v67
	v_fma_f32 v41, v41, v69, v67
	v_exp_f32_e32 v38, v38
	v_exp_f32_e32 v39, v39
	v_exp_f32_e32 v40, v40
; #define LAS __attribute__((address_space(3)))
; __device__ __forceinline__ unsigned cvt_pk_bf16(float lo, float hi) { const f32x2 v = {lo, hi}; const bf16x2_t r = __builtin_convertvector(v, bf16x2_t); return __builtin_bit_cast(unsigned, r); }
; __device__ __forceinline__ f32x4 mfma16(bf16x8 a, bf16x8 b, f32x4 c) { return __builtin_amdgcn_mfma_f32_16x16x32_bf16(a, b, c, 0, 0, 0); }
; __device__ __forceinline__ void xa_pair(LAS unsigned char* lds, const bf16_t* Ux, const bf16_t* Kb, const bf16_t* Vt, bf16_t* Yx, int pair, int tid) {
;     ...
;         for (int nt = 0; nt < 16; ++nt)
; #pragma unroll
;             for (int j = 0; j < 4; ++j) { const float pz = exp2f((s[nt][j] - mx) * sc); s[nt][j] = pz; l += pz; }
;         l += __shfl_xor(l, 16); l += __shfl_xor(l, 32);
;         f32x4 o[8];
; #pragma unroll
;         for (int dt = 0; dt < 8; ++dt) o[dt] = (f32x4){0.f, 0.f, 0.f, 0.f};
; #pragma unroll
;         for (int c = 0; c < 8; ++c) { union { u32x4 u; bf16x8 v; } pf;
;             pf.u.x = cvt_pk_bf16(s[2 * c][0], s[2 * c][1]); pf.u.y = cvt_pk_bf16(s[2 * c][2], s[2 * c][3]); pf.u.z = cvt_pk_bf16(s[2 * c + 1][0], s[2 * c + 1][1]); pf.u.w = cvt_pk_bf16(s[2 * c + 1][2], s[2 * c + 1][3]);
; #pragma unroll
;             for (int dt = 0; dt < 8; ++dt) { LAS const unsigned char* vr = lds + XV_OFF + (16 * dt + fr) * XV_STRIDE + (32 * c + 4 * fq) * 2; union { u32x4 u; bf16x8 v; } vf;
;                 const u32x2 lo = *(LAS const u32x2*)vr, hi = *(LAS const u32x2*)(vr + 32); vf.u.x = lo.x; vf.u.y = lo.y; vf.u.z = hi.x; vf.u.w = hi.y;
;                 o[dt] = mfma16(vf.v, pf.v, o[dt]); }
	v_exp_f32_e32 v41, v41
	v_fma_f32 v34, v34, v69, v67
	v_fma_f32 v35, v35, v69, v67
	v_fma_f32 v36, v36, v69, v67
	v_fma_f32 v37, v37, v69, v67
	v_exp_f32_e32 v34, v34
	v_exp_f32_e32 v35, v35
	v_exp_f32_e32 v36, v36
	v_exp_f32_e32 v37, v37
	v_fma_f32 v30, v30, v69, v67
	v_fma_f32 v31, v31, v69, v67
	v_fma_f32 v32, v32, v69, v67
	v_fma_f32 v33, v33, v69, v67
	v_exp_f32_e32 v30, v30
	v_exp_f32_e32 v31, v31
	v_exp_f32_e32 v32, v32
	v_exp_f32_e32 v33, v33
	v_fma_f32 v26, v26, v69, v67
	v_fma_f32 v27, v27, v69, v67
	v_fma_f32 v28, v28, v69, v67
	v_fma_f32 v29, v29, v69, v67
	v_exp_f32_e32 v26, v26
	v_exp_f32_e32 v27, v27
	v_exp_f32_e32 v28, v28
	v_exp_f32_e32 v29, v29
	v_fma_f32 v22, v22, v69, v67
	v_fma_f32 v23, v23, v69, v67
	v_fma_f32 v24, v24, v69, v67
	v_fma_f32 v25, v25, v69, v67
	v_exp_f32_e32 v22, v22
	v_exp_f32_e32 v23, v23
	v_exp_f32_e32 v24, v24
	v_exp_f32_e32 v25, v25
	v_fma_f32 v18, v18, v69, v67
	v_fma_f32 v19, v19, v69, v67
	v_fma_f32 v20, v20, v69, v67
	v_fma_f32 v21, v21, v69, v67
	v_exp_f32_e32 v18, v18
	v_exp_f32_e32 v19, v19
	v_exp_f32_e32 v20, v20
	v_exp_f32_e32 v21, v21
	v_fma_f32 v10, v10, v69, v67
	v_fma_f32 v11, v11, v69, v67
	v_fma_f32 v12, v12, v69, v67
	v_fma_f32 v13, v13, v69, v67
	v_exp_f32_e32 v10, v10
	v_exp_f32_e32 v11, v11
	v_exp_f32_e32 v12, v12
	v_exp_f32_e32 v13, v13
	v_fma_f32 v2, v2, v69, v67
	v_fma_f32 v3, v3, v69, v67
	v_fma_f32 v4, v4, v69, v67
	v_fma_f32 v5, v5, v69, v67
	v_exp_f32_e32 v2, v2
	v_exp_f32_e32 v3, v3
	v_exp_f32_e32 v4, v4
	v_exp_f32_e32 v5, v5
	v_fma_f32 v14, v14, v69, v67
	v_fma_f32 v15, v15, v69, v67
	v_fma_f32 v16, v16, v69, v67
	v_fma_f32 v17, v17, v69, v67
	v_exp_f32_e32 v14, v14
	v_exp_f32_e32 v15, v15
	v_exp_f32_e32 v16, v16
	v_exp_f32_e32 v17, v17
	v_fma_f32 v6, v6, v69, v67
	v_fma_f32 v7, v7, v69, v67
	v_fma_f32 v8, v8, v69, v67
	v_fma_f32 v9, v9, v69, v67
	v_exp_f32_e32 v6, v6
	v_exp_f32_e32 v7, v7
	v_exp_f32_e32 v8, v8
	v_exp_f32_e32 v9, v9
	v_fma_f32 v54, v54, v69, v67
	v_fma_f32 v55, v55, v69, v67
	v_fma_f32 v56, v56, v69, v67
	v_fma_f32 v57, v57, v69, v67
	v_exp_f32_e32 v54, v54
	v_exp_f32_e32 v55, v55
	v_exp_f32_e32 v56, v56
	v_exp_f32_e32 v57, v57
	s_nop 0
	v_pk_add_f32 v[70:71], v[58:59], v[46:47]
	v_pk_add_f32 v[72:73], v[60:61], v[48:49]
	v_pk_add_f32 v[70:71], v[70:71], v[62:63]
	v_pk_add_f32 v[72:73], v[72:73], v[64:65]
	v_pk_add_f32 v[70:71], v[70:71], v[50:51]
	v_pk_add_f32 v[72:73], v[72:73], v[52:53]
	v_pk_add_f32 v[70:71], v[70:71], v[42:43]
	v_pk_add_f32 v[72:73], v[72:73], v[44:45]
	v_pk_add_f32 v[70:71], v[70:71], v[38:39]
	v_pk_add_f32 v[72:73], v[72:73], v[40:41]
	v_pk_add_f32 v[70:71], v[70:71], v[34:35]
	v_pk_add_f32 v[72:73], v[72:73], v[36:37]
	v_pk_add_f32 v[70:71], v[70:71], v[30:31]
	v_pk_add_f32 v[72:73], v[72:73], v[32:33]
	v_pk_add_f32 v[70:71], v[70:71], v[26:27]
	v_pk_add_f32 v[72:73], v[72:73], v[28:29]
	v_pk_add_f32 v[70:71], v[70:71], v[22:23]
	v_pk_add_f32 v[72:73], v[72:73], v[24:25]
	v_pk_add_f32 v[70:71], v[70:71], v[18:19]
	v_pk_add_f32 v[72:73], v[72:73], v[20:21]
	v_pk_add_f32 v[70:71], v[70:71], v[10:11]
	v_pk_add_f32 v[72:73], v[72:73], v[12:13]
	v_pk_add_f32 v[70:71], v[70:71], v[2:3]
	v_pk_add_f32 v[72:73], v[72:73], v[4:5]
	v_pk_add_f32 v[70:71], v[70:71], v[14:15]
	v_pk_add_f32 v[72:73], v[72:73], v[16:17]
	v_pk_add_f32 v[70:71], v[70:71], v[6:7]
	v_pk_add_f32 v[72:73], v[72:73], v[8:9]
	v_pk_add_f32 v[70:71], v[70:71], v[54:55]
	v_pk_add_f32 v[72:73], v[72:73], v[56:57]
	v_pk_add_f32 v[70:71], v[70:71], v[72:73]
	s_nop 0
	v_add_f32_e32 v68, v70, v71
	ds_bpermute_b32 v75, v124, v68
	s_waitcnt lgkmcnt(0)
	v_add_f32_e32 v68, v68, v75
	ds_bpermute_b32 v75, v125, v68
	v_cvt_pk_bf16_f32 v58, v58, v59
	v_cvt_pk_bf16_f32 v59, v60, v61
	v_cvt_pk_bf16_f32 v60, v46, v47
	v_cvt_pk_bf16_f32 v61, v48, v49
	v_cvt_pk_bf16_f32 v62, v62, v63
	v_cvt_pk_bf16_f32 v63, v64, v65
	v_cvt_pk_bf16_f32 v64, v50, v51
	v_cvt_pk_bf16_f32 v65, v52, v53
	v_cvt_pk_bf16_f32 v42, v42, v43
	v_cvt_pk_bf16_f32 v43, v44, v45
	v_cvt_pk_bf16_f32 v44, v38, v39
	v_cvt_pk_bf16_f32 v45, v40, v41
	v_cvt_pk_bf16_f32 v34, v34, v35
	v_cvt_pk_bf16_f32 v35, v36, v37
	v_cvt_pk_bf16_f32 v36, v30, v31
	v_cvt_pk_bf16_f32 v37, v32, v33
	v_cvt_pk_bf16_f32 v26, v26, v27
	v_cvt_pk_bf16_f32 v27, v28, v29
	v_cvt_pk_bf16_f32 v28, v22, v23
	v_cvt_pk_bf16_f32 v29, v24, v25
	v_cvt_pk_bf16_f32 v18, v18, v19
	v_cvt_pk_bf16_f32 v19, v20, v21
	v_cvt_pk_bf16_f32 v20, v10, v11
	v_cvt_pk_bf16_f32 v21, v12, v13
	v_cvt_pk_bf16_f32 v2, v2, v3
	v_cvt_pk_bf16_f32 v3, v4, v5
	v_cvt_pk_bf16_f32 v4, v14, v15
	v_cvt_pk_bf16_f32 v5, v16, v17
	v_cvt_pk_bf16_f32 v6, v6, v7
	v_cvt_pk_bf16_f32 v7, v8, v9
	v_cvt_pk_bf16_f32 v8, v54, v55
	v_cvt_pk_bf16_f32 v9, v56, v57
	s_waitcnt lgkmcnt(0)
	v_add_f32_e32 v68, v68, v75
	s_waitcnt lgkmcnt(8)
	v_mfma_f32_16x16x32_bf16 v[46:49], v[164:167], v[58:61], 0
	v_mfma_f32_16x16x32_bf16 v[50:53], v[168:171], v[58:61], 0
	v_mfma_f32_16x16x32_bf16 v[38:41], v[172:175], v[58:61], 0
	v_mfma_f32_16x16x32_bf16 v[30:33], v[176:179], v[58:61], 0
	ds_read2_b64 v[164:167], v224 offset0:8 offset1:12
	ds_read2_b64 v[168:171], v225 offset0:8 offset1:12
	ds_read2_b64 v[172:175], v226 offset0:8 offset1:12
	ds_read2_b64 v[176:179], v227 offset0:8 offset1:12
	s_waitcnt lgkmcnt(8)
	v_mfma_f32_16x16x32_bf16 v[22:25], v[180:183], v[58:61], 0
	v_mfma_f32_16x16x32_bf16 v[10:13], v[184:187], v[58:61], 0
	v_mfma_f32_16x16x32_bf16 v[14:17], v[188:191], v[58:61], 0
	v_mfma_f32_16x16x32_bf16 v[54:57], v[192:195], v[58:61], 0
	ds_read2_b64 v[180:183], v220 offset0:16 offset1:20
	ds_read2_b64 v[184:187], v221 offset0:16 offset1:20
	ds_read2_b64 v[188:191], v222 offset0:16 offset1:20
	ds_read2_b64 v[192:195], v223 offset0:16 offset1:20
	s_waitcnt lgkmcnt(8)
; #define LAS __attribute__((address_space(3)))
; __device__ __forceinline__ unsigned cvt_pk_bf16(float lo, float hi) { const f32x2 v = {lo, hi}; const bf16x2_t r = __builtin_convertvector(v, bf16x2_t); return __builtin_bit_cast(unsigned, r); }
; __device__ __forceinline__ f32x4 mfma16(bf16x8 a, bf16x8 b, f32x4 c) { return __builtin_amdgcn_mfma_f32_16x16x32_bf16(a, b, c, 0, 0, 0); }
; __device__ __forceinline__ void xa_pair(LAS unsigned char* lds, const bf16_t* Ux, const bf16_t* Kb, const bf16_t* Vt, bf16_t* Yx, int pair, int tid) {
;     ...
;         for (int c = 0; c < 8; ++c) { union { u32x4 u; bf16x8 v; } pf;
;             pf.u.x = cvt_pk_bf16(s[2 * c][0], s[2 * c][1]); pf.u.y = cvt_pk_bf16(s[2 * c][2], s[2 * c][3]); pf.u.z = cvt_pk_bf16(s[2 * c + 1][0], s[2 * c + 1][1]); pf.u.w = cvt_pk_bf16(s[2 * c + 1][2], s[2 * c + 1][3]);
; #pragma unroll
;             for (int dt = 0; dt < 8; ++dt) { LAS const unsigned char* vr = lds + XV_OFF + (16 * dt + fr) * XV_STRIDE + (32 * c + 4 * fq) * 2; union { u32x4 u; bf16x8 v; } vf;
;                 const u32x2 lo = *(LAS const u32x2*)vr, hi = *(LAS const u32x2*)(vr + 32); vf.u.x = lo.x; vf.u.y = lo.y; vf.u.z = hi.x; vf.u.w = hi.y;
;                 o[dt] = mfma16(vf.v, pf.v, o[dt]); }
;             asm volatile("" ::: "memory"); }
	v_mfma_f32_16x16x32_bf16 v[46:49], v[196:199], v[62:65], v[46:49]
	v_mfma_f32_16x16x32_bf16 v[50:53], v[200:203], v[62:65], v[50:53]
	v_mfma_f32_16x16x32_bf16 v[38:41], v[204:207], v[62:65], v[38:41]
	v_mfma_f32_16x16x32_bf16 v[30:33], v[212:215], v[62:65], v[30:33]
	ds_read2_b64 v[196:199], v224 offset0:16 offset1:20
	ds_read2_b64 v[200:203], v225 offset0:16 offset1:20
	ds_read2_b64 v[204:207], v226 offset0:16 offset1:20
	ds_read2_b64 v[212:215], v227 offset0:16 offset1:20
	s_waitcnt lgkmcnt(8)
	v_mfma_f32_16x16x32_bf16 v[22:25], v[164:167], v[62:65], v[22:25]
	v_mfma_f32_16x16x32_bf16 v[10:13], v[168:171], v[62:65], v[10:13]
	v_mfma_f32_16x16x32_bf16 v[14:17], v[172:175], v[62:65], v[14:17]
	v_mfma_f32_16x16x32_bf16 v[54:57], v[176:179], v[62:65], v[54:57]
	ds_read2_b64 v[164:167], v220 offset0:24 offset1:28
	ds_read2_b64 v[168:171], v221 offset0:24 offset1:28
	ds_read2_b64 v[172:175], v222 offset0:24 offset1:28
	ds_read2_b64 v[176:179], v223 offset0:24 offset1:28
	s_waitcnt lgkmcnt(8)
	v_mfma_f32_16x16x32_bf16 v[46:49], v[180:183], v[42:45], v[46:49]
	v_mfma_f32_16x16x32_bf16 v[50:53], v[184:187], v[42:45], v[50:53]
	v_mfma_f32_16x16x32_bf16 v[38:41], v[188:191], v[42:45], v[38:41]
	v_mfma_f32_16x16x32_bf16 v[30:33], v[192:195], v[42:45], v[30:33]
	ds_read2_b64 v[180:183], v224 offset0:24 offset1:28
	ds_read2_b64 v[184:187], v225 offset0:24 offset1:28
	ds_read2_b64 v[188:191], v226 offset0:24 offset1:28
	ds_read2_b64 v[192:195], v227 offset0:24 offset1:28
	s_waitcnt lgkmcnt(8)
	v_mfma_f32_16x16x32_bf16 v[22:25], v[196:199], v[42:45], v[22:25]
	v_mfma_f32_16x16x32_bf16 v[10:13], v[200:203], v[42:45], v[10:13]
	v_mfma_f32_16x16x32_bf16 v[14:17], v[204:207], v[42:45], v[14:17]
	v_mfma_f32_16x16x32_bf16 v[54:57], v[212:215], v[42:45], v[54:57]
	ds_read2_b64 v[196:199], v220 offset0:32 offset1:36
	ds_read2_b64 v[200:203], v221 offset0:32 offset1:36
	ds_read2_b64 v[204:207], v222 offset0:32 offset1:36
	ds_read2_b64 v[212:215], v223 offset0:32 offset1:36
	s_waitcnt lgkmcnt(8)
	v_mfma_f32_16x16x32_bf16 v[46:49], v[164:167], v[34:37], v[46:49]
	v_mfma_f32_16x16x32_bf16 v[50:53], v[168:171], v[34:37], v[50:53]
	v_mfma_f32_16x16x32_bf16 v[38:41], v[172:175], v[34:37], v[38:41]
	v_mfma_f32_16x16x32_bf16 v[30:33], v[176:179], v[34:37], v[30:33]
	ds_read2_b64 v[164:167], v224 offset0:32 offset1:36
	ds_read2_b64 v[168:171], v225 offset0:32 offset1:36
	ds_read2_b64 v[172:175], v226 offset0:32 offset1:36
	ds_read2_b64 v[176:179], v227 offset0:32 offset1:36
	s_waitcnt lgkmcnt(8)
	v_mfma_f32_16x16x32_bf16 v[22:25], v[180:183], v[34:37], v[22:25]
	v_mfma_f32_16x16x32_bf16 v[10:13], v[184:187], v[34:37], v[10:13]
	v_mfma_f32_16x16x32_bf16 v[14:17], v[188:191], v[34:37], v[14:17]
	v_mfma_f32_16x16x32_bf16 v[54:57], v[192:195], v[34:37], v[54:57]
	ds_read2_b64 v[180:183], v220 offset0:40 offset1:44
	ds_read2_b64 v[184:187], v221 offset0:40 offset1:44
	ds_read2_b64 v[188:191], v222 offset0:40 offset1:44
	ds_read2_b64 v[192:195], v223 offset0:40 offset1:44
	s_waitcnt lgkmcnt(8)
	v_mfma_f32_16x16x32_bf16 v[46:49], v[196:199], v[26:29], v[46:49]
	v_mfma_f32_16x16x32_bf16 v[50:53], v[200:203], v[26:29], v[50:53]
	v_mfma_f32_16x16x32_bf16 v[38:41], v[204:207], v[26:29], v[38:41]
	v_mfma_f32_16x16x32_bf16 v[30:33], v[212:215], v[26:29], v[30:33]
	ds_read2_b64 v[196:199], v224 offset0:40 offset1:44
	ds_read2_b64 v[200:203], v225 offset0:40 offset1:44
	ds_read2_b64 v[204:207], v226 offset0:40 offset1:44
	ds_read2_b64 v[212:215], v227 offset0:40 offset1:44
	s_waitcnt lgkmcnt(8)
	v_mfma_f32_16x16x32_bf16 v[22:25], v[164:167], v[26:29], v[22:25]
	v_mfma_f32_16x16x32_bf16 v[10:13], v[168:171], v[26:29], v[10:13]
	v_mfma_f32_16x16x32_bf16 v[14:17], v[172:175], v[26:29], v[14:17]
	v_mfma_f32_16x16x32_bf16 v[54:57], v[176:179], v[26:29], v[54:57]
	ds_read2_b64 v[164:167], v220 offset0:48 offset1:52
	ds_read2_b64 v[168:171], v221 offset0:48 offset1:52
	ds_read2_b64 v[172:175], v222 offset0:48 offset1:52
	ds_read2_b64 v[176:179], v223 offset0:48 offset1:52
	s_waitcnt lgkmcnt(8)
	v_mfma_f32_16x16x32_bf16 v[46:49], v[180:183], v[18:21], v[46:49]
	v_mfma_f32_16x16x32_bf16 v[50:53], v[184:187], v[18:21], v[50:53]
	v_mfma_f32_16x16x32_bf16 v[38:41], v[188:191], v[18:21], v[38:41]
	v_mfma_f32_16x16x32_bf16 v[30:33], v[192:195], v[18:21], v[30:33]
	ds_read2_b64 v[180:183], v224 offset0:48 offset1:52
	ds_read2_b64 v[184:187], v225 offset0:48 offset1:52
	ds_read2_b64 v[188:191], v226 offset0:48 offset1:52
	ds_read2_b64 v[192:195], v227 offset0:48 offset1:52
	s_waitcnt lgkmcnt(8)
; #define LAS __attribute__((address_space(3)))
; __device__ __forceinline__ unsigned cvt_pk_bf16(float lo, float hi) { const f32x2 v = {lo, hi}; const bf16x2_t r = __builtin_convertvector(v, bf16x2_t); return __builtin_bit_cast(unsigned, r); }
; __device__ __forceinline__ void st_bf4(bf16_t* p, f32x4 v) { u32x2 w; w.x = cvt_pk_bf16(v[0], v[1]); w.y = cvt_pk_bf16(v[2], v[3]); *(u32x2*)p = w; }
; __device__ __forceinline__ f32x4 mfma16(bf16x8 a, bf16x8 b, f32x4 c) { return __builtin_amdgcn_mfma_f32_16x16x32_bf16(a, b, c, 0, 0, 0); }
; __device__ __forceinline__ void xa_pair(LAS unsigned char* lds, const bf16_t* Ux, const bf16_t* Kb, const bf16_t* Vt, bf16_t* Yx, int pair, int tid) {
;     ...
;         for (int c = 0; c < 8; ++c) { union { u32x4 u; bf16x8 v; } pf;
;             pf.u.x = cvt_pk_bf16(s[2 * c][0], s[2 * c][1]); pf.u.y = cvt_pk_bf16(s[2 * c][2], s[2 * c][3]); pf.u.z = cvt_pk_bf16(s[2 * c + 1][0], s[2 * c + 1][1]); pf.u.w = cvt_pk_bf16(s[2 * c + 1][2], s[2 * c + 1][3]);
; #pragma unroll
;             for (int dt = 0; dt < 8; ++dt) { LAS const unsigned char* vr = lds + XV_OFF + (16 * dt + fr) * XV_STRIDE + (32 * c + 4 * fq) * 2; union { u32x4 u; bf16x8 v; } vf;
;                 const u32x2 lo = *(LAS const u32x2*)vr, hi = *(LAS const u32x2*)(vr + 32); vf.u.x = lo.x; vf.u.y = lo.y; vf.u.z = hi.x; vf.u.w = hi.y;
;                 o[dt] = mfma16(vf.v, pf.v, o[dt]); }
;             asm volatile("" ::: "memory"); }
;         const float il = 1.0f / l;
; #pragma unroll
;         for (int dt = 0; dt < 8; ++dt) st_bf4(Yx + (size_t)t * 512 + h * 128 + 16 * dt + 4 * fq, o[dt] * il);
	v_mfma_f32_16x16x32_bf16 v[22:25], v[196:199], v[18:21], v[22:25]
	v_mfma_f32_16x16x32_bf16 v[10:13], v[200:203], v[18:21], v[10:13]
	v_mfma_f32_16x16x32_bf16 v[14:17], v[204:207], v[18:21], v[14:17]
	v_mfma_f32_16x16x32_bf16 v[54:57], v[212:215], v[18:21], v[54:57]
	ds_read2_b64 v[196:199], v220 offset0:56 offset1:60
	ds_read2_b64 v[200:203], v221 offset0:56 offset1:60
	ds_read2_b64 v[204:207], v222 offset0:56 offset1:60
	ds_read2_b64 v[212:215], v223 offset0:56 offset1:60
	s_waitcnt lgkmcnt(8)
	v_mfma_f32_16x16x32_bf16 v[46:49], v[164:167], v[2:5], v[46:49]
	v_mfma_f32_16x16x32_bf16 v[50:53], v[168:171], v[2:5], v[50:53]
	v_mfma_f32_16x16x32_bf16 v[38:41], v[172:175], v[2:5], v[38:41]
	v_mfma_f32_16x16x32_bf16 v[30:33], v[176:179], v[2:5], v[30:33]
	ds_read2_b64 v[164:167], v224 offset0:56 offset1:60
	ds_read2_b64 v[168:171], v225 offset0:56 offset1:60
	ds_read2_b64 v[172:175], v226 offset0:56 offset1:60
	ds_read2_b64 v[176:179], v227 offset0:56 offset1:60
	s_waitcnt lgkmcnt(8)
	v_mfma_f32_16x16x32_bf16 v[22:25], v[180:183], v[2:5], v[22:25]
	v_mfma_f32_16x16x32_bf16 v[10:13], v[184:187], v[2:5], v[10:13]
	v_mfma_f32_16x16x32_bf16 v[14:17], v[188:191], v[2:5], v[14:17]
	v_mfma_f32_16x16x32_bf16 v[54:57], v[192:195], v[2:5], v[54:57]
	s_waitcnt lgkmcnt(4)
	v_mfma_f32_16x16x32_bf16 v[46:49], v[196:199], v[6:9], v[46:49]
	v_mfma_f32_16x16x32_bf16 v[50:53], v[200:203], v[6:9], v[50:53]
	v_mfma_f32_16x16x32_bf16 v[38:41], v[204:207], v[6:9], v[38:41]
	v_mfma_f32_16x16x32_bf16 v[30:33], v[212:215], v[6:9], v[30:33]
	s_waitcnt lgkmcnt(0)
	v_mfma_f32_16x16x32_bf16 v[22:25], v[164:167], v[6:9], v[22:25]
	v_mfma_f32_16x16x32_bf16 v[10:13], v[168:171], v[6:9], v[10:13]
	v_mfma_f32_16x16x32_bf16 v[14:17], v[172:175], v[6:9], v[14:17]
	v_mfma_f32_16x16x32_bf16 v[54:57], v[176:179], v[6:9], v[54:57]
	v_div_scale_f32 v75, s[8:9], v68, v68, 1.0
	v_rcp_f32_e32 v76, v75
	s_movk_i32 s8, 0x80
	v_fma_f32 v77, -v75, v76, 1.0
	v_fmac_f32_e32 v76, v77, v76
	v_div_scale_f32 v77, vcc, 1.0, v68, 1.0
	v_mul_f32_e32 v70, v77, v76
	v_fma_f32 v71, -v75, v70, v77
	v_fmac_f32_e32 v70, v71, v76
	v_fma_f32 v75, -v75, v70, v77
	v_div_fmas_f32 v75, v75, v76, v70
	v_div_fixup_f32 v74, v75, v68, 1.0
	v_lshl_add_u64 v[72:73], v[112:113], 0, v[114:115]
	v_pk_mul_f32 v[46:47], v[74:75], v[46:47] op_sel_hi:[0,1]
	v_pk_mul_f32 v[48:49], v[74:75], v[48:49] op_sel_hi:[0,1]
	v_cvt_pk_bf16_f32 v46, v46, v47
	v_cvt_pk_bf16_f32 v47, v48, v49
	global_store_dwordx2 v[72:73], v[46:47], off
	v_pk_mul_f32 v[50:51], v[74:75], v[50:51] op_sel_hi:[0,1]
	v_pk_mul_f32 v[52:53], v[74:75], v[52:53] op_sel_hi:[0,1]
	v_cvt_pk_bf16_f32 v50, v50, v51
	v_cvt_pk_bf16_f32 v51, v52, v53
	global_store_dwordx2 v[72:73], v[50:51], off offset:32
	v_pk_mul_f32 v[38:39], v[74:75], v[38:39] op_sel_hi:[0,1]
	v_pk_mul_f32 v[40:41], v[74:75], v[40:41] op_sel_hi:[0,1]
	v_cvt_pk_bf16_f32 v38, v38, v39
	v_cvt_pk_bf16_f32 v39, v40, v41
	global_store_dwordx2 v[72:73], v[38:39], off offset:64
	v_pk_mul_f32 v[30:31], v[74:75], v[30:31] op_sel_hi:[0,1]
	v_pk_mul_f32 v[32:33], v[74:75], v[32:33] op_sel_hi:[0,1]
	v_cvt_pk_bf16_f32 v30, v30, v31
	v_cvt_pk_bf16_f32 v31, v32, v33
	global_store_dwordx2 v[72:73], v[30:31], off offset:96
	v_pk_mul_f32 v[22:23], v[74:75], v[22:23] op_sel_hi:[0,1]
	v_pk_mul_f32 v[24:25], v[74:75], v[24:25] op_sel_hi:[0,1]
	v_cvt_pk_bf16_f32 v22, v22, v23
	v_cvt_pk_bf16_f32 v23, v24, v25
	global_store_dwordx2 v[72:73], v[22:23], off offset:128
	v_pk_mul_f32 v[10:11], v[74:75], v[10:11] op_sel_hi:[0,1]
	v_pk_mul_f32 v[12:13], v[74:75], v[12:13] op_sel_hi:[0,1]
	v_cvt_pk_bf16_f32 v10, v10, v11
	v_cvt_pk_bf16_f32 v11, v12, v13
	global_store_dwordx2 v[72:73], v[10:11], off offset:160
	v_pk_mul_f32 v[14:15], v[74:75], v[14:15] op_sel_hi:[0,1]
	v_pk_mul_f32 v[16:17], v[74:75], v[16:17] op_sel_hi:[0,1]
	v_cvt_pk_bf16_f32 v14, v14, v15
	v_cvt_pk_bf16_f32 v15, v16, v17
	global_store_dwordx2 v[72:73], v[14:15], off offset:192
	v_pk_mul_f32 v[54:55], v[74:75], v[54:55] op_sel_hi:[0,1]
	v_pk_mul_f32 v[56:57], v[74:75], v[56:57] op_sel_hi:[0,1]
	v_cvt_pk_bf16_f32 v54, v54, v55
	v_cvt_pk_bf16_f32 v55, v56, v57
	global_store_dwordx2 v[72:73], v[54:55], off offset:224
	s_and_b64 vcc, exec, s[6:7]
	s_mov_b64 s[6:7], 0
	s_cbranch_vccnz .LBB0_318
	s_mov_b32 s11, 1
	s_and_b64 vcc, exec, s[4:5]
	s_barrier
	s_cbranch_vccz .LBB0_317
	s_mov_b64 s[4:5], 0
